# G1 K-loop: LDS-DMA staging rebalanced 2/6/2/6 -> 4/4/4/4 pieces per super-phase (Bs[.][1] stage moved one super-phase later, vmcnt 8/6/8/6)
# speedup vs baseline: 1.0545x; 1.0113x over previous
.LBB0_110:
	v_lshrrev_b32_e32 v18, 1, v8
	v_and_b32_e32 v18, 24, v18
	v_and_b32_e32 v9, 15, v8
	v_lshlrev_b32_e32 v19, 1, v18
	v_lshlrev_b32_e32 v8, 2, v8
	v_lshl_or_b32 v142, s38, 6, v9
	v_lshl_or_b32 v9, v9, 6, v19
	s_lshl_b32 s8, s38, 13
	v_and_b32_e32 v8, 32, v8
	v_bitop3_b32 v19, v9, s8, v8 bitop3:0xde
	s_lshl_b32 s8, s25, 5
	s_and_b32 s10, s8, 0x60
	v_lshl_add_u64 v[10:11], s[56:57], 0, v[0:1]
	v_mov_b32_e32 v131, v1
	v_readlane_b32 s50, v254, 48
	s_lshl_b32 s8, s10, 7
	v_lshl_add_u64 v[12:13], s[56:57], 0, v[130:131]
	v_mov_b32_e32 v135, v1
	v_readlane_b32 s51, v254, 49
	v_bitop3_b32 v143, v9, s8, v8 bitop3:0xde
	s_add_i32 m0, s53, 0x18000
	v_lshl_add_u64 v[8:9], v[10:11], 0, s[26:27]
	v_lshl_add_u64 v[14:15], s[50:51], 0, v[134:135]
	v_mov_b32_e32 v133, v1
	s_waitcnt vmcnt(2)
	s_barrier
	global_load_lds_dwordx4 v[8:9], off
	v_lshl_add_u64 v[8:9], v[12:13], 0, s[26:27]
	s_add_i32 m0, s53, 0x1a000
	s_add_i32 s61, s53, 0x8000
	s_add_i32 s62, s53, 0xa000
	v_lshl_add_u64 v[16:17], s[50:51], 0, v[132:133]
	global_load_lds_dwordx4 v[8:9], off
	v_lshl_add_u64 v[8:9], v[14:15], 0, s[26:27]
	s_mov_b32 m0, s61
	s_add_u32 s8, s56, 0x40080
	global_load_lds_dwordx4 v[8:9], off
	v_lshl_add_u64 v[8:9], v[16:17], 0, s[26:27]
	s_mov_b32 m0, s62
	s_addc_u32 s9, s57, 0
	s_mov_b64 s[100:101], s[8:9]
	global_load_lds_dwordx4 v[8:9], off
	s_cmpk_lt_u32 s24, 0x100
	v_lshlrev_b32_e32 v8, 14, v6
	v_and_b32_e32 v8, 0xffff8000, v8
	v_lshl_add_u32 v5, v5, 11, v8
	v_and_b32_e32 v6, 1, v6
	v_lshl_or_b32 v5, v6, 6, v5
	v_lshl_add_u32 v136, v7, 1, v5
	v_lshlrev_b32_e32 v5, 14, v2
	v_and_b32_e32 v5, 0xffff8000, v5
	s_waitcnt vmcnt(4)
	v_lshl_add_u32 v3, v3, 11, v5
	v_and_b32_e32 v2, 1, v2
	v_lshl_or_b32 v2, v2, 6, v3
	v_readlane_b32 s8, v254, 46
	s_cselect_b64 s[24:25], -1, 0
	v_or_b32_e32 v144, s10, v18
	v_mov_b32_e32 v137, v1
	v_lshl_add_u32 v138, v4, 1, v2
	v_mov_b32_e32 v139, v1
	s_mov_b32 s63, 0
	v_add_u32_e32 v145, 0, v19
	v_readlane_b32 s64, v254, 52
	s_mov_b32 s65, s8
	s_barrier
	v_readlane_b32 s9, v254, 47
	s_branch .LBB0_113

.LBB0_120:
	s_add_u32 s8, s50, 0xfffc0080
	s_addc_u32 s9, s51, -1
	s_add_i32 s10, 0, 0x10000
	s_cmp_eq_u32 s72, 12
	s_cselect_b32 s57, s43, s9
	s_cselect_b32 s56, s66, s8
	v_add_u32_e32 v140, s10, v143
	s_cselect_b32 s55, s41, s69
	s_cselect_b32 s54, s67, s68
	s_add_i32 s11, 0, 0x14000
	ds_read_b128 v[146:149], v140
	ds_read_b128 v[150:153], v140 offset:1024
	ds_read_b128 v[154:157], v140 offset:2048
	ds_read_b128 v[158:161], v140 offset:3072
	v_add_u32_e32 v140, s11, v143
	ds_read_b128 v[162:165], v140
	ds_read_b128 v[166:169], v140 offset:1024
	ds_read_b128 v[170:173], v140 offset:2048
	ds_read_b128 v[174:177], v140 offset:3072
	v_lshl_add_u64 v[140:141], s[100:101], 0, v[0:1]
	s_add_i32 m0, s52, 0x1c000
	s_nop 0
	global_load_lds_dwordx4 v[140:141], off
	v_lshl_add_u64 v[140:141], s[100:101], 0, v[130:131]
	s_add_i32 m0, s52, 0x1e000
	s_nop 0
	global_load_lds_dwordx4 v[140:141], off
	v_lshl_add_u64 v[140:141], s[50:51], 0, v[136:137]
	s_add_i32 m0, s53, 0xc000
	ds_read_b128 v[178:181], v145
	ds_read_b128 v[182:185], v145 offset:1024
	ds_read_b128 v[224:227], v145 offset:2048
	ds_read_b128 v[228:231], v145 offset:3072
	ds_read_b128 v[232:235], v145 offset:4096
	ds_read_b128 v[236:239], v145 offset:5120
	ds_read_b128 v[240:243], v145 offset:6144
	ds_read_b128 v[244:247], v145 offset:7168
	global_load_lds_dwordx4 v[140:141], off
	v_lshl_add_u64 v[140:141], s[50:51], 0, v[138:139]
	s_add_i32 m0, s53, 0xe000
	s_nop 0
	global_load_lds_dwordx4 v[140:141], off
	s_waitcnt vmcnt(8)
	s_waitcnt lgkmcnt(0)
	s_barrier
	s_setprio 1
	s_waitcnt lgkmcnt(0)
	v_mfma_f32_16x16x32_bf16 v[126:129], v[146:149], v[178:181], v[126:129]
	v_mfma_f32_16x16x32_bf16 v[118:121], v[154:157], v[178:181], v[118:121]
	v_mfma_f32_16x16x32_bf16 v[110:113], v[146:149], v[224:227], v[110:113]
	v_mfma_f32_16x16x32_bf16 v[102:105], v[154:157], v[224:227], v[102:105]
	v_mfma_f32_16x16x32_bf16 v[94:97], v[146:149], v[232:235], v[94:97]
	v_mfma_f32_16x16x32_bf16 v[86:89], v[154:157], v[232:235], v[86:89]
	v_mfma_f32_16x16x32_bf16 v[78:81], v[146:149], v[240:243], v[78:81]
	v_mfma_f32_16x16x32_bf16 v[70:73], v[154:157], v[240:243], v[70:73]
	v_mfma_f32_16x16x32_bf16 v[126:129], v[150:153], v[182:185], v[126:129]
	v_mfma_f32_16x16x32_bf16 v[118:121], v[158:161], v[182:185], v[118:121]
	v_mfma_f32_16x16x32_bf16 v[110:113], v[150:153], v[228:231], v[110:113]
	v_mfma_f32_16x16x32_bf16 v[102:105], v[158:161], v[228:231], v[102:105]
	v_mfma_f32_16x16x32_bf16 v[94:97], v[150:153], v[236:239], v[94:97]
	v_mfma_f32_16x16x32_bf16 v[86:89], v[158:161], v[236:239], v[86:89]
	v_mfma_f32_16x16x32_bf16 v[78:81], v[150:153], v[244:247], v[78:81]
	v_mfma_f32_16x16x32_bf16 v[70:73], v[158:161], v[244:247], v[70:73]
	s_setprio 0
	s_setprio 1
	v_mfma_f32_16x16x32_bf16 v[122:125], v[162:165], v[178:181], v[122:125]
	v_mfma_f32_16x16x32_bf16 v[114:117], v[170:173], v[178:181], v[114:117]
	v_mfma_f32_16x16x32_bf16 v[106:109], v[162:165], v[224:227], v[106:109]
	v_mfma_f32_16x16x32_bf16 v[98:101], v[170:173], v[224:227], v[98:101]
	v_mfma_f32_16x16x32_bf16 v[90:93], v[162:165], v[232:235], v[90:93]
	v_mfma_f32_16x16x32_bf16 v[82:85], v[170:173], v[232:235], v[82:85]
	v_mfma_f32_16x16x32_bf16 v[74:77], v[162:165], v[240:243], v[74:77]
	v_mfma_f32_16x16x32_bf16 v[66:69], v[170:173], v[240:243], v[66:69]
	v_mfma_f32_16x16x32_bf16 v[122:125], v[166:169], v[182:185], v[122:125]
	v_mfma_f32_16x16x32_bf16 v[114:117], v[174:177], v[182:185], v[114:117]
	v_mfma_f32_16x16x32_bf16 v[106:109], v[166:169], v[228:231], v[106:109]
	v_mfma_f32_16x16x32_bf16 v[98:101], v[174:177], v[228:231], v[98:101]
	v_mfma_f32_16x16x32_bf16 v[90:93], v[166:169], v[236:239], v[90:93]
	v_mfma_f32_16x16x32_bf16 v[82:85], v[174:177], v[236:239], v[82:85]
	v_mfma_f32_16x16x32_bf16 v[74:77], v[166:169], v[244:247], v[74:77]
	v_mfma_f32_16x16x32_bf16 v[66:69], v[174:177], v[244:247], v[66:69]
	s_setprio 0
	s_barrier
	s_add_i32 s8, s10, s52
	v_lshl_add_u64 v[140:141], s[54:55], 0, v[0:1]
	s_mov_b32 m0, s8
	ds_read_b128 v[178:181], v145 offset:16384
	ds_read_b128 v[182:185], v145 offset:17408
	ds_read_b128 v[224:227], v145 offset:18432
	ds_read_b128 v[228:231], v145 offset:19456
	ds_read_b128 v[232:235], v145 offset:20480
	ds_read_b128 v[236:239], v145 offset:21504
	ds_read_b128 v[240:243], v145 offset:22528
	ds_read_b128 v[244:247], v145 offset:23552
	global_load_lds_dwordx4 v[140:141], off
	s_add_i32 m0, s8, 0x2000
	v_lshl_add_u64 v[186:187], s[54:55], 0, v[130:131]
	global_load_lds_dwordx4 v[186:187], off
	v_lshl_add_u64 v[248:249], s[56:57], 0, v[132:133]
	v_lshl_add_u64 v[202:203], s[56:57], 0, v[134:135]
	s_mov_b32 m0, s53
	s_nop 0
	global_load_lds_dwordx4 v[202:203], off
	s_mov_b32 m0, s58
	s_nop 0
	global_load_lds_dwordx4 v[248:249], off
	s_waitcnt vmcnt(6)
	s_waitcnt lgkmcnt(0)
	s_barrier
	s_setprio 1
	s_waitcnt lgkmcnt(0)
	v_mfma_f32_16x16x32_bf16 v[62:65], v[146:149], v[178:181], v[62:65]
	v_mfma_f32_16x16x32_bf16 v[54:57], v[154:157], v[178:181], v[54:57]
	v_mfma_f32_16x16x32_bf16 v[46:49], v[146:149], v[224:227], v[46:49]
	v_mfma_f32_16x16x32_bf16 v[38:41], v[154:157], v[224:227], v[38:41]
	v_mfma_f32_16x16x32_bf16 v[30:33], v[146:149], v[232:235], v[30:33]
	v_mfma_f32_16x16x32_bf16 v[22:25], v[154:157], v[232:235], v[22:25]
	v_mfma_f32_16x16x32_bf16 v[14:17], v[146:149], v[240:243], v[14:17]
	v_mfma_f32_16x16x32_bf16 v[6:9], v[154:157], v[240:243], v[6:9]
	v_mfma_f32_16x16x32_bf16 v[62:65], v[150:153], v[182:185], v[62:65]
	v_mfma_f32_16x16x32_bf16 v[54:57], v[158:161], v[182:185], v[54:57]
	v_mfma_f32_16x16x32_bf16 v[46:49], v[150:153], v[228:231], v[46:49]
	v_mfma_f32_16x16x32_bf16 v[38:41], v[158:161], v[228:231], v[38:41]
	v_mfma_f32_16x16x32_bf16 v[30:33], v[150:153], v[236:239], v[30:33]
	v_mfma_f32_16x16x32_bf16 v[22:25], v[158:161], v[236:239], v[22:25]
	v_mfma_f32_16x16x32_bf16 v[14:17], v[150:153], v[244:247], v[14:17]
	v_mfma_f32_16x16x32_bf16 v[6:9], v[158:161], v[244:247], v[6:9]
	s_setprio 0
	s_setprio 1
	v_mfma_f32_16x16x32_bf16 v[58:61], v[162:165], v[178:181], v[58:61]
	v_mfma_f32_16x16x32_bf16 v[50:53], v[170:173], v[178:181], v[50:53]
	v_mfma_f32_16x16x32_bf16 v[42:45], v[162:165], v[224:227], v[42:45]
	v_mfma_f32_16x16x32_bf16 v[34:37], v[170:173], v[224:227], v[34:37]
	v_mfma_f32_16x16x32_bf16 v[26:29], v[162:165], v[232:235], v[26:29]
	v_mfma_f32_16x16x32_bf16 v[18:21], v[170:173], v[232:235], v[18:21]
	v_mfma_f32_16x16x32_bf16 v[10:13], v[162:165], v[240:243], v[10:13]
	v_mfma_f32_16x16x32_bf16 v[2:5], v[170:173], v[240:243], v[2:5]
	v_mfma_f32_16x16x32_bf16 v[58:61], v[166:169], v[182:185], v[58:61]
	v_mfma_f32_16x16x32_bf16 v[50:53], v[174:177], v[182:185], v[50:53]
	v_mfma_f32_16x16x32_bf16 v[42:45], v[166:169], v[228:231], v[42:45]
	v_mfma_f32_16x16x32_bf16 v[34:37], v[174:177], v[228:231], v[34:37]
	v_mfma_f32_16x16x32_bf16 v[26:29], v[166:169], v[236:239], v[26:29]
	v_mfma_f32_16x16x32_bf16 v[18:21], v[174:177], v[236:239], v[18:21]
	v_mfma_f32_16x16x32_bf16 v[10:13], v[166:169], v[244:247], v[10:13]
	v_mfma_f32_16x16x32_bf16 v[2:5], v[174:177], v[244:247], v[2:5]
	s_setprio 0
	s_barrier
	s_add_i32 s10, 0, 0x18000
	s_add_i32 s11, 0, 0x1c000
	v_add_u32_e32 v158, s10, v143
	v_add_u32_e32 v174, s11, v143
	ds_read_b128 v[146:149], v158
	ds_read_b128 v[150:153], v158 offset:1024
	ds_read_b128 v[154:157], v158 offset:2048
	ds_read_b128 v[158:161], v158 offset:3072
	ds_read_b128 v[162:165], v174
	ds_read_b128 v[166:169], v174 offset:1024
	ds_read_b128 v[170:173], v174 offset:2048
	ds_read_b128 v[174:177], v174 offset:3072
	s_add_u32 s100, s54, 0x40000
	s_addc_u32 s101, s55, 0
	v_lshl_add_u64 v[250:251], s[100:101], 0, v[0:1]
	s_add_i32 m0, s52, 0x14000
	s_nop 0
	global_load_lds_dwordx4 v[250:251], off
	v_lshl_add_u64 v[250:251], s[100:101], 0, v[130:131]
	s_add_i32 m0, s52, 0x16000
	s_nop 0
	global_load_lds_dwordx4 v[250:251], off
	s_add_u32 s8, s56, 0x40000
	s_addc_u32 s9, s57, 0
	s_mov_b32 m0, s59
	v_lshl_add_u64 v[250:251], s[8:9], 0, v[134:135]
	ds_read_b128 v[178:181], v145 offset:32768
	ds_read_b128 v[182:185], v145 offset:33792
	ds_read_b128 v[224:227], v145 offset:34816
	ds_read_b128 v[228:231], v145 offset:35840
	ds_read_b128 v[232:235], v145 offset:36864
	ds_read_b128 v[236:239], v145 offset:37888
	ds_read_b128 v[240:243], v145 offset:38912
	ds_read_b128 v[244:247], v145 offset:39936
	global_load_lds_dwordx4 v[250:251], off
	v_lshl_add_u64 v[250:251], s[8:9], 0, v[132:133]
	s_mov_b32 m0, s60
	s_nop 0
	global_load_lds_dwordx4 v[250:251], off
	s_waitcnt vmcnt(8)
	s_waitcnt lgkmcnt(0)
	s_barrier
	s_setprio 1
	s_waitcnt lgkmcnt(0)
	v_mfma_f32_16x16x32_bf16 v[126:129], v[146:149], v[178:181], v[126:129]
	v_mfma_f32_16x16x32_bf16 v[118:121], v[154:157], v[178:181], v[118:121]
	v_mfma_f32_16x16x32_bf16 v[110:113], v[146:149], v[224:227], v[110:113]
	v_mfma_f32_16x16x32_bf16 v[102:105], v[154:157], v[224:227], v[102:105]
	v_mfma_f32_16x16x32_bf16 v[94:97], v[146:149], v[232:235], v[94:97]
	v_mfma_f32_16x16x32_bf16 v[86:89], v[154:157], v[232:235], v[86:89]
	v_mfma_f32_16x16x32_bf16 v[78:81], v[146:149], v[240:243], v[78:81]
	v_mfma_f32_16x16x32_bf16 v[70:73], v[154:157], v[240:243], v[70:73]
	v_mfma_f32_16x16x32_bf16 v[126:129], v[150:153], v[182:185], v[126:129]
	v_mfma_f32_16x16x32_bf16 v[118:121], v[158:161], v[182:185], v[118:121]
	v_mfma_f32_16x16x32_bf16 v[110:113], v[150:153], v[228:231], v[110:113]
	v_mfma_f32_16x16x32_bf16 v[102:105], v[158:161], v[228:231], v[102:105]
	v_mfma_f32_16x16x32_bf16 v[94:97], v[150:153], v[236:239], v[94:97]
	v_mfma_f32_16x16x32_bf16 v[86:89], v[158:161], v[236:239], v[86:89]
	v_mfma_f32_16x16x32_bf16 v[78:81], v[150:153], v[244:247], v[78:81]
	v_mfma_f32_16x16x32_bf16 v[70:73], v[158:161], v[244:247], v[70:73]
	s_setprio 0
	s_setprio 1
	v_mfma_f32_16x16x32_bf16 v[122:125], v[162:165], v[178:181], v[122:125]
	v_mfma_f32_16x16x32_bf16 v[114:117], v[170:173], v[178:181], v[114:117]
	v_mfma_f32_16x16x32_bf16 v[106:109], v[162:165], v[224:227], v[106:109]
	v_mfma_f32_16x16x32_bf16 v[98:101], v[170:173], v[224:227], v[98:101]
	v_mfma_f32_16x16x32_bf16 v[90:93], v[162:165], v[232:235], v[90:93]
	v_mfma_f32_16x16x32_bf16 v[82:85], v[170:173], v[232:235], v[82:85]
	v_mfma_f32_16x16x32_bf16 v[74:77], v[162:165], v[240:243], v[74:77]
	v_mfma_f32_16x16x32_bf16 v[66:69], v[170:173], v[240:243], v[66:69]
	v_mfma_f32_16x16x32_bf16 v[122:125], v[166:169], v[182:185], v[122:125]
	v_mfma_f32_16x16x32_bf16 v[114:117], v[174:177], v[182:185], v[114:117]
	v_mfma_f32_16x16x32_bf16 v[106:109], v[166:169], v[228:231], v[106:109]
	v_mfma_f32_16x16x32_bf16 v[98:101], v[174:177], v[228:231], v[98:101]
	v_mfma_f32_16x16x32_bf16 v[90:93], v[166:169], v[236:239], v[90:93]
	v_mfma_f32_16x16x32_bf16 v[82:85], v[174:177], v[236:239], v[82:85]
	v_mfma_f32_16x16x32_bf16 v[74:77], v[166:169], v[244:247], v[74:77]
	v_mfma_f32_16x16x32_bf16 v[66:69], v[174:177], v[244:247], v[66:69]
	s_setprio 0
	s_barrier
	s_add_i32 s8, s10, s52
	v_lshl_add_u64 v[140:141], v[140:141], 0, s[26:27]
	s_mov_b32 m0, s8
	ds_read_b128 v[178:181], v145 offset:49152
	ds_read_b128 v[182:185], v145 offset:50176
	ds_read_b128 v[224:227], v145 offset:51200
	ds_read_b128 v[228:231], v145 offset:52224
	ds_read_b128 v[232:235], v145 offset:53248
	ds_read_b128 v[236:239], v145 offset:54272
	ds_read_b128 v[240:243], v145 offset:55296
	ds_read_b128 v[244:247], v145 offset:56320
	global_load_lds_dwordx4 v[140:141], off
	s_add_i32 m0, s8, 0x2000
	s_add_u32 s100, s54, 0x40080
	s_addc_u32 s101, s55, 0
	v_lshl_add_u64 v[140:141], v[186:187], 0, s[26:27]
	global_load_lds_dwordx4 v[140:141], off
	v_lshl_add_u64 v[140:141], v[202:203], 0, s[26:27]
	s_mov_b32 m0, s61
	s_nop 0
	global_load_lds_dwordx4 v[140:141], off
	v_lshl_add_u64 v[140:141], v[248:249], 0, s[26:27]
	s_mov_b32 m0, s62
	s_nop 0
	global_load_lds_dwordx4 v[140:141], off
	s_waitcnt vmcnt(6)
	s_waitcnt lgkmcnt(0)
	s_barrier
	s_setprio 1
	s_waitcnt lgkmcnt(0)
	v_mfma_f32_16x16x32_bf16 v[62:65], v[146:149], v[178:181], v[62:65]
	v_mfma_f32_16x16x32_bf16 v[54:57], v[154:157], v[178:181], v[54:57]
	v_mfma_f32_16x16x32_bf16 v[46:49], v[146:149], v[224:227], v[46:49]
	v_mfma_f32_16x16x32_bf16 v[38:41], v[154:157], v[224:227], v[38:41]
	v_mfma_f32_16x16x32_bf16 v[30:33], v[146:149], v[232:235], v[30:33]
	v_mfma_f32_16x16x32_bf16 v[22:25], v[154:157], v[232:235], v[22:25]
	v_mfma_f32_16x16x32_bf16 v[14:17], v[146:149], v[240:243], v[14:17]
	v_mfma_f32_16x16x32_bf16 v[6:9], v[154:157], v[240:243], v[6:9]
	v_mfma_f32_16x16x32_bf16 v[62:65], v[150:153], v[182:185], v[62:65]
	v_mfma_f32_16x16x32_bf16 v[54:57], v[158:161], v[182:185], v[54:57]
	v_mfma_f32_16x16x32_bf16 v[46:49], v[150:153], v[228:231], v[46:49]
	v_mfma_f32_16x16x32_bf16 v[38:41], v[158:161], v[228:231], v[38:41]
	v_mfma_f32_16x16x32_bf16 v[30:33], v[150:153], v[236:239], v[30:33]
	v_mfma_f32_16x16x32_bf16 v[22:25], v[158:161], v[236:239], v[22:25]
	v_mfma_f32_16x16x32_bf16 v[14:17], v[150:153], v[244:247], v[14:17]
	v_mfma_f32_16x16x32_bf16 v[6:9], v[158:161], v[244:247], v[6:9]
	s_setprio 0
	s_setprio 1
	v_mfma_f32_16x16x32_bf16 v[58:61], v[162:165], v[178:181], v[58:61]
	v_mfma_f32_16x16x32_bf16 v[50:53], v[170:173], v[178:181], v[50:53]
	v_mfma_f32_16x16x32_bf16 v[42:45], v[162:165], v[224:227], v[42:45]
	v_mfma_f32_16x16x32_bf16 v[34:37], v[170:173], v[224:227], v[34:37]
	v_mfma_f32_16x16x32_bf16 v[26:29], v[162:165], v[232:235], v[26:29]
	v_mfma_f32_16x16x32_bf16 v[18:21], v[170:173], v[232:235], v[18:21]
	v_mfma_f32_16x16x32_bf16 v[10:13], v[162:165], v[240:243], v[10:13]
	v_mfma_f32_16x16x32_bf16 v[2:5], v[170:173], v[240:243], v[2:5]
	v_mfma_f32_16x16x32_bf16 v[58:61], v[166:169], v[182:185], v[58:61]
	v_mfma_f32_16x16x32_bf16 v[50:53], v[174:177], v[182:185], v[50:53]
	v_mfma_f32_16x16x32_bf16 v[42:45], v[166:169], v[228:231], v[42:45]
	v_mfma_f32_16x16x32_bf16 v[34:37], v[174:177], v[228:231], v[34:37]
	v_mfma_f32_16x16x32_bf16 v[26:29], v[166:169], v[236:239], v[26:29]
	v_mfma_f32_16x16x32_bf16 v[18:21], v[174:177], v[236:239], v[18:21]
	v_mfma_f32_16x16x32_bf16 v[10:13], v[166:169], v[244:247], v[10:13]
	v_mfma_f32_16x16x32_bf16 v[2:5], v[174:177], v[244:247], v[2:5]
	s_setprio 0
	s_barrier
	s_add_i32 s72, s72, 2
	s_add_u32 s50, s50, 0x100
	s_addc_u32 s51, s51, 0
	s_add_u32 s68, s68, 0x100
	s_addc_u32 s69, s69, 0
	s_cmp_gt_u32 s72, 13
	s_cbranch_scc0 .LBB0_120
	s_and_b64 vcc, exec, s[24:25]
	s_mov_b64 s[68:69], s[36:37]
	s_cbranch_vccz .LBB0_123
	s_barrier

	.amdhsa_kernel _Z6mk_fwd4Args
		.amdhsa_group_segment_fixed_size 4096
		.amdhsa_private_segment_fixed_size 0
		.amdhsa_kernarg_size 480
		.amdhsa_user_sgpr_count 2
		.amdhsa_user_sgpr_dispatch_ptr 0
		.amdhsa_user_sgpr_queue_ptr 0
		.amdhsa_user_sgpr_kernarg_segment_ptr 1
		.amdhsa_user_sgpr_dispatch_id 0
		.amdhsa_user_sgpr_kernarg_preload_length 0
		.amdhsa_user_sgpr_kernarg_preload_offset 0
		.amdhsa_user_sgpr_private_segment_size 0
		.amdhsa_uses_dynamic_stack 0
		.amdhsa_enable_private_segment 0
		.amdhsa_system_sgpr_workgroup_id_x 1
		.amdhsa_system_sgpr_workgroup_id_y 0
		.amdhsa_system_sgpr_workgroup_id_z 0
		.amdhsa_system_sgpr_workgroup_info 0
		.amdhsa_system_vgpr_workitem_id 2
		.amdhsa_next_free_vgpr 256
		.amdhsa_next_free_sgpr 102
		.amdhsa_accum_offset 256
		.amdhsa_reserve_vcc 1
		.amdhsa_float_round_mode_32 0
		.amdhsa_float_round_mode_16_64 0
		.amdhsa_float_denorm_mode_32 3
		.amdhsa_float_denorm_mode_16_64 3
		.amdhsa_dx10_clamp 1
		.amdhsa_ieee_mode 1
		.amdhsa_fp16_overflow 0
		.amdhsa_tg_split 0
		.amdhsa_exception_fp_ieee_invalid_op 0
		.amdhsa_exception_fp_denorm_src 0
		.amdhsa_exception_fp_ieee_div_zero 0
		.amdhsa_exception_fp_ieee_overflow 0
		.amdhsa_exception_fp_ieee_underflow 0
		.amdhsa_exception_fp_ieee_inexact 0
		.amdhsa_exception_int_div_zero 0
	.end_amdhsa_kernel

amdhsa.kernels:
  - .agpr_count:     0
    .args:
      - .offset:         0
        .size:           224
        .value_kind:     by_value
      - .offset:         224
        .size:           4
        .value_kind:     hidden_block_count_x
      - .offset:         228
        .size:           4
        .value_kind:     hidden_block_count_y
      - .offset:         232
        .size:           4
        .value_kind:     hidden_block_count_z
      - .offset:         236
        .size:           2
        .value_kind:     hidden_group_size_x
      - .offset:         238
        .size:           2
        .value_kind:     hidden_group_size_y
      - .offset:         240
        .size:           2
        .value_kind:     hidden_group_size_z
      - .offset:         242
        .size:           2
        .value_kind:     hidden_remainder_x
      - .offset:         244
        .size:           2
        .value_kind:     hidden_remainder_y
      - .offset:         246
        .size:           2
        .value_kind:     hidden_remainder_z
      - .offset:         264
        .size:           8
        .value_kind:     hidden_global_offset_x
      - .offset:         272
        .size:           8
        .value_kind:     hidden_global_offset_y
      - .offset:         280
        .size:           8
        .value_kind:     hidden_global_offset_z
      - .offset:         288
        .size:           2
        .value_kind:     hidden_grid_dims
      - .offset:         312
        .size:           8
        .value_kind:     hidden_multigrid_sync_arg
      - .offset:         344
        .size:           4
        .value_kind:     hidden_dynamic_lds_size
    .group_segment_fixed_size: 4096
    .kernarg_segment_align: 8
    .kernarg_segment_size: 480
    .language:       OpenCL C
    .language_version:
      - 2
      - 0
    .max_flat_workgroup_size: 512
    .name:           _Z6mk_fwd4Args
    .private_segment_fixed_size: 0
    .sgpr_count:     108
    .sgpr_spill_count: 191
    .symbol:         _Z6mk_fwd4Args.kd
    .uniform_work_group_size: 1
    .uses_dynamic_stack: false
    .vgpr_count:     256
    .vgpr_spill_count: 0
    .wavefront_size: 64
